# adds p0 row loop with two rows (8 loads) in flight and interleaved lane-sum chains
# speedup vs baseline: 1.0022x; 1.0022x over previous
.LBB0_7:
.LBB0_8:
	s_waitcnt lgkmcnt(0)
	global_load_dwordx4 v[14:17], v[6:7], off offset:-3072
	global_load_dwordx4 v[18:21], v[6:7], off offset:-2048
	global_load_dwordx4 v[22:25], v[6:7], off offset:-1024
	global_load_dwordx4 v[26:29], v[6:7], off
	v_lshl_add_u64 v[50:51], v[6:7], 0, s[18:19]
	global_load_dwordx4 v[32:35], v[50:51], off offset:-3072
	global_load_dwordx4 v[36:39], v[50:51], off offset:-2048
	global_load_dwordx4 v[40:43], v[50:51], off offset:-1024
	global_load_dwordx4 v[44:47], v[50:51], off
	v_lshl_add_u64 v[52:53], v[4:5], 0, s[16:17]
	v_lshl_add_u64 v[54:55], v[2:3], 0, s[14:15]
	v_lshl_add_u64 v[56:57], s[10:11], 0, v[4:5]
	v_add_co_u32_e32 v56, vcc, s13, v56
	s_nop 1
	v_addc_co_u32_e32 v57, vcc, 0, v57, vcc
	v_lshl_add_u64 v[48:49], s[10:11], 0, v[52:53]
	v_add_co_u32_e32 v48, vcc, s13, v48
	s_nop 1
	v_addc_co_u32_e32 v49, vcc, 0, v49, vcc
	s_waitcnt vmcnt(7)
	v_cvt_pk_bf16_f32 v60, v14, v15
	v_cvt_pk_bf16_f32 v61, v16, v17
	global_store_dwordx2 v[56:57], v[60:61], off
	v_mul_f32_e32 v58, v15, v15
	v_mul_f32_e32 v59, v17, v17
	v_fmac_f32_e32 v58, v14, v14
	v_fmac_f32_e32 v59, v16, v16
	v_add_f32_e32 v30, v58, v59
	s_waitcnt vmcnt(7)
	v_cvt_pk_bf16_f32 v60, v18, v19
	v_cvt_pk_bf16_f32 v61, v20, v21
	global_store_dwordx2 v[56:57], v[60:61], off offset:512
	v_mul_f32_e32 v58, v19, v19
	v_mul_f32_e32 v59, v21, v21
	v_fmac_f32_e32 v58, v18, v18
	v_fmac_f32_e32 v59, v20, v20
	v_add_f32_e32 v58, v58, v59
	v_add_f32_e32 v30, v30, v58
	s_waitcnt vmcnt(7)
	v_cvt_pk_bf16_f32 v60, v22, v23
	v_cvt_pk_bf16_f32 v61, v24, v25
	global_store_dwordx2 v[56:57], v[60:61], off offset:1024
	v_mul_f32_e32 v58, v23, v23
	v_mul_f32_e32 v59, v25, v25
	v_fmac_f32_e32 v58, v22, v22
	v_fmac_f32_e32 v59, v24, v24
	v_add_f32_e32 v58, v58, v59
	v_add_f32_e32 v30, v30, v58
	s_waitcnt vmcnt(7)
	v_cvt_pk_bf16_f32 v60, v26, v27
	v_cvt_pk_bf16_f32 v61, v28, v29
	global_store_dwordx2 v[56:57], v[60:61], off offset:1536
	v_mul_f32_e32 v58, v27, v27
	v_mul_f32_e32 v59, v29, v29
	v_fmac_f32_e32 v58, v26, v26
	v_fmac_f32_e32 v59, v28, v28
	v_add_f32_e32 v58, v58, v59
	v_add_f32_e32 v30, v30, v58
	s_waitcnt vmcnt(7)
	v_cvt_pk_bf16_f32 v64, v32, v33
	v_cvt_pk_bf16_f32 v65, v34, v35
	global_store_dwordx2 v[48:49], v[64:65], off
	v_mul_f32_e32 v62, v33, v33
	v_mul_f32_e32 v63, v35, v35
	v_fmac_f32_e32 v62, v32, v32
	v_fmac_f32_e32 v63, v34, v34
	v_add_f32_e32 v31, v62, v63
	s_waitcnt vmcnt(7)
	v_cvt_pk_bf16_f32 v64, v36, v37
	v_cvt_pk_bf16_f32 v65, v38, v39
	global_store_dwordx2 v[48:49], v[64:65], off offset:512
	v_mul_f32_e32 v62, v37, v37
	v_mul_f32_e32 v63, v39, v39
	v_fmac_f32_e32 v62, v36, v36
	v_fmac_f32_e32 v63, v38, v38
	v_add_f32_e32 v62, v62, v63
	v_add_f32_e32 v31, v31, v62
	s_waitcnt vmcnt(7)
	v_cvt_pk_bf16_f32 v64, v40, v41
	v_cvt_pk_bf16_f32 v65, v42, v43
	global_store_dwordx2 v[48:49], v[64:65], off offset:1024
	v_mul_f32_e32 v62, v41, v41
	v_mul_f32_e32 v63, v43, v43
	v_fmac_f32_e32 v62, v40, v40
	v_fmac_f32_e32 v63, v42, v42
	v_add_f32_e32 v62, v62, v63
	v_add_f32_e32 v31, v31, v62
	s_waitcnt vmcnt(7)
	v_cvt_pk_bf16_f32 v64, v44, v45
	v_cvt_pk_bf16_f32 v65, v46, v47
	global_store_dwordx2 v[48:49], v[64:65], off offset:1536
	v_mul_f32_e32 v62, v45, v45
	v_mul_f32_e32 v63, v47, v47
	v_fmac_f32_e32 v62, v44, v44
	v_fmac_f32_e32 v63, v46, v46
	v_add_f32_e32 v62, v62, v63
	v_add_f32_e32 v31, v31, v62
	ds_bpermute_b32 v58, v8, v30
	ds_bpermute_b32 v59, v8, v31
	s_waitcnt lgkmcnt(1)
	v_add_f32_e32 v30, v30, v58
	s_waitcnt lgkmcnt(0)
	v_add_f32_e32 v31, v31, v59
	ds_bpermute_b32 v58, v9, v30
	ds_bpermute_b32 v59, v9, v31
	s_waitcnt lgkmcnt(1)
	v_add_f32_e32 v30, v30, v58
	s_waitcnt lgkmcnt(0)
	v_add_f32_e32 v31, v31, v59
	ds_bpermute_b32 v58, v10, v30
	ds_bpermute_b32 v59, v10, v31
	s_waitcnt lgkmcnt(1)
	v_add_f32_e32 v30, v30, v58
	s_waitcnt lgkmcnt(0)
	v_add_f32_e32 v31, v31, v59
	ds_bpermute_b32 v58, v11, v30
	ds_bpermute_b32 v59, v11, v31
	s_waitcnt lgkmcnt(1)
	v_add_f32_e32 v30, v30, v58
	s_waitcnt lgkmcnt(0)
	v_add_f32_e32 v31, v31, v59
	ds_bpermute_b32 v58, v12, v30
	ds_bpermute_b32 v59, v12, v31
	s_waitcnt lgkmcnt(1)
	v_add_f32_e32 v30, v30, v58
	s_waitcnt lgkmcnt(0)
	v_add_f32_e32 v31, v31, v59
	ds_bpermute_b32 v58, v13, v30
	ds_bpermute_b32 v59, v13, v31
	s_waitcnt lgkmcnt(1)
	v_add_f32_e32 v30, v30, v58
	s_waitcnt lgkmcnt(0)
	v_add_f32_e32 v31, v31, v59
	s_mov_b64 s[20:21], exec
	s_and_b64 exec, exec, s[2:3]
	v_cndmask_b32_e64 v58, 0, v30, s[4:5]
	v_cndmask_b32_e64 v59, 0, v31, s[4:5]
	v_lshl_add_u64 v[60:61], s[10:11], 0, v[2:3]
	v_lshl_add_u64 v[62:63], s[10:11], 0, v[54:55]
	global_store_dword v[60:61], v58, off
	global_store_dword v[62:63], v59, off
	s_mov_b64 exec, s[20:21]
	v_readlane_b32 s20, v248, 21
	s_lshl_b32 s20, s20, 1
	s_add_i32 s12, s12, s20
	v_lshl_add_u64 v[2:3], v[54:55], 0, s[14:15]
	v_lshl_add_u64 v[4:5], v[52:53], 0, s[16:17]
	v_lshl_add_u64 v[6:7], v[50:51], 0, s[18:19]
	s_cmpk_gt_i32 s12, 0x7fff
	v_readlane_b32 s20, v248, 21
	v_readlane_b32 s21, v248, 22
	s_cbranch_scc0 .LBB0_8
